# DSA attention: selection mask folded into the QK^T MFMA chain -- the score accumulators start from a 16-entry LDS table (0 / -inf per selected bit nibble) instead of 0; the 32 per-step bit ops are gon
# speedup vs baseline: 1.0035x; 1.0035x over previous
; #define LAS __attribute__((address_space(3)))
; __device__ __forceinline__ void dsa_attn_item(CParams& p, LAS unsigned char* lds, int b, int qb, int tid_in, int wave) {
;     ...
;     const int hd = wave & 3, qs = wave >> 2, r = lane & 31, hh = lane >> 5;
;     const int tb0 = b * SEQ; const int q0 = qb * 64 + 32 * qs;
;     for (int i = tid; i < 4 * 132; i += NTHREADS) bdl[i] = bd[i];
;     h16x8 qf[8];
; #pragma unroll
;     for (int s = 0; s < 8; ++s) qf[s] = *(const h16x8*)(proj + (size_t)(tb0 + q0 + r) * OD_N + 1536 + hd * 128 + 16 * s + 8 * hh);
;     f32x16 o[4];
; #pragma unroll
;     for (int d = 0; d < 4; ++d)
; #pragma unroll
;         for (int i = 0; i < 16; ++i) o[d][i] = 0.f;
;     float m_run = -INFINITY, l_run = 0.f;
;     const int qp = q0 + r;
;     const int vlo = r * 72 + ((hh ^ (r >> 3)) << 2), vhi = r * 72 + (((hh ^ (r >> 3)) ^ 2) << 2);
;     const unsigned long long* bmq = bm + (size_t)(tb0 + qp) * 64;
;     const LAS float* bdh = bdl + hd * 132;
;     const int nkt = qb + 1;
;     h16x8 pk[2], pv[2];
; #pragma unroll
;     for (int i = 0; i < 2; ++i) { const int key = i * 32 + (tid >> 4), ch = tid & 15;
;         pk[i] = *(const h16x8*)(proj + (size_t)(tb0 + key) * OD_N + 2048 + ch * 8);
;         pv[i] = *(const h16x8*)(proj + (size_t)(tb0 + key) * OD_N + 2176 + ch * 8); }
;     ATT_STAGE(0, 2048, 2176, 1);
;     unsigned long long mkn = bmq[0];
;     __syncthreads();
.LBB0_510:
	s_or_b64 exec, exec, s[4:5]
	s_mov_b32 s100, 0
	v_add_u32_e32 v145, s84, v183
	v_and_b32_e32 v80, 31, v16
	v_add_u32_e32 v0, s58, v145
	v_bfe_u32 v81, v16, 5, 1
	v_or_b32_e32 v144, v80, v0
	v_mad_i64_i32 v[2:3], s[4:5], v144, s33, v[142:143]
	v_lshlrev_b32_e32 v0, 4, v81
	v_lshl_add_u64 v[34:35], v[2:3], 0, v[0:1]
	v_or_b32_e32 v0, v80, v145
	v_add_u32_e32 v14, s58, v0
	v_ashrrev_i32_e32 v17, 4, v16
	v_lshlrev_b32_e32 v0, 3, v16
	v_add_u32_e32 v147, s58, v17
	v_and_b32_e32 v0, 0x78, v0
	v_mov_b64_e32 v[36:37], s[14:15]
	v_mad_i64_i32 v[18:19], s[4:5], v147, s33, v[36:37]
	v_lshlrev_b32_e32 v0, 1, v0
	v_add_u32_e32 v22, 32, v147
	v_lshl_add_u64 v[18:19], v[18:19], 0, v[0:1]
	v_mad_i64_i32 v[22:23], s[4:5], v22, s33, v[36:37]
	v_add_co_u32_e32 v26, vcc, s3, v18
	s_min_i32 s4, s83, 1
	s_nop 0
	v_addc_co_u32_e32 v27, vcc, 0, v19, vcc
	v_lshl_add_u64 v[22:23], v[22:23], 0, v[0:1]
	v_lshl_add_u32 v40, s4, 6, v147
	v_add_co_u32_e32 v30, vcc, s3, v22
	v_mad_i64_i32 v[32:33], s[4:5], v40, s33, v[36:37]
	s_nop 0
	v_addc_co_u32_e32 v31, vcc, 0, v23, vcc
	v_lshl_add_u64 v[32:33], v[32:33], 0, v[0:1]
	v_add_u32_e32 v40, 32, v40
	v_add_co_u32_e32 v38, vcc, s3, v32
	v_mad_i64_i32 v[36:37], s[4:5], v40, s33, v[36:37]
	v_ashrrev_i32_e32 v15, 31, v14
	v_addc_co_u32_e32 v39, vcc, 0, v33, vcc
	v_lshl_add_u64 v[36:37], v[36:37], 0, v[0:1]
	global_load_dwordx4 v[2:5], v[34:35], off offset:3104
	global_load_dwordx4 v[6:9], v[34:35], off offset:3136
	global_load_dwordx4 v[10:13], v[34:35], off offset:3168
	global_load_dwordx4 v[96:99], v[34:35], off offset:3200
	global_load_dwordx4 v[100:103], v[34:35], off offset:3232
	global_load_dwordx4 v[104:107], v[34:35], off offset:3264
	v_lshlrev_b64 v[14:15], 9, v[14:15]
	global_load_dwordx4 v[108:111], v[34:35], off offset:3296
	global_load_dwordx4 v[18:21], v[26:27], off
	global_load_dwordx4 v[22:25], v[30:31], off
	s_nop 0
	global_load_dwordx4 v[26:29], v[26:27], off offset:256
	v_add_co_u32_e32 v36, vcc, 0x1000, v36
	v_lshl_add_u64 v[14:15], s[16:17], 0, v[14:15]
	global_load_dwordx4 v[30:33], v[30:31], off offset:256
	s_nop 0
	global_load_dwordx4 v[116:119], v[38:39], off
	v_addc_co_u32_e32 v37, vcc, 0, v37, vcc
	global_load_dwordx4 v[120:123], v[38:39], off offset:256
	global_load_dwordx4 v[128:131], v[36:37], off
	global_load_dwordx4 v[112:115], v[34:35], off offset:3072
	global_load_dwordx2 v[150:151], v[14:15], off
	global_load_dwordx4 v[124:127], v[36:37], off offset:256
	v_and_b32_e32 v16, 15, v16
	v_lshlrev_b32_e32 v34, 2, v16
	v_lshlrev_b32_e32 v35, 1, v17
	v_lshl_add_u32 v153, v16, 4, 0
	v_mul_u32_u24_e32 v155, 0x480, v16
	v_and_b32_e32 v16, 6, v35
	v_bfe_u32 v36, v17, 2, 1
	v_bfe_u32 v37, v17, 3, 1
	v_and_b32_e32 v38, -13, v17
	v_lshl_or_b32 v38, v36, 3, v38
	v_lshl_or_b32 v38, v37, 2, v38
	v_and_b32_e32 v34, 0x38, v34
	v_bitop3_b32 v36, v38, v34, -4 bitop3:0x6c
	v_mul_lo_u32 v154, v17, s97
	v_add_u32_e32 v162, 0, v16
	v_lshlrev_b32_e32 v163, 1, v36
	v_add_u32_e32 v35, v153, v154
	v_add3_u32 v16, v162, v163, v155
	s_mov_b64 s[4:5], -1
	s_cmp_gt_i32 s83, -1
	v_lshlrev_b32_e32 v152, 2, v81
	s_waitcnt vmcnt(9)
	ds_write_b128 v35, v[18:21]
	s_waitcnt vmcnt(7)
	ds_write_b16 v16, v26 offset:34816
	ds_write_b16_d16_hi v16, v26 offset:34960
	ds_write_b16 v16, v27 offset:35104
	ds_write_b16_d16_hi v16, v27 offset:35248
	ds_write_b16 v16, v28 offset:35392
	ds_write_b16_d16_hi v16, v28 offset:35536
	ds_write_b16 v16, v29 offset:35680
	ds_write_b16_d16_hi v16, v29 offset:35824
	v_add_u32_e32 v16, 32, v38
	v_bitop3_b32 v16, v16, v34, -4 bitop3:0x6c
	v_lshlrev_b32_e32 v164, 1, v16
	v_add3_u32 v16, v162, v164, v155
	ds_write_b128 v35, v[22:25] offset:8704
	s_waitcnt vmcnt(6)
	ds_write_b16 v16, v30 offset:34816
	ds_write_b16_d16_hi v16, v30 offset:34960
	ds_write_b16 v16, v31 offset:35104
	ds_write_b16_d16_hi v16, v31 offset:35248
	ds_write_b16 v16, v32 offset:35392
	ds_write_b16_d16_hi v16, v32 offset:35536
	ds_write_b16 v16, v33 offset:35680
	ds_write_b16_d16_hi v16, v33 offset:35824
	v_and_b32_e32 v240, 15, v80
	v_bfe_i32 v236, v240, 0, 1
	v_not_b32_e32 v236, v236
	v_and_b32_e32 v236, 0xff800000, v236
	v_bfe_i32 v237, v240, 1, 1
	v_not_b32_e32 v237, v237
	v_and_b32_e32 v237, 0xff800000, v237
	v_bfe_i32 v238, v240, 2, 1
	v_not_b32_e32 v238, v238
	v_and_b32_e32 v238, 0xff800000, v238
	v_bfe_i32 v239, v240, 3, 1
	v_not_b32_e32 v239, v239
	v_and_b32_e32 v239, 0xff800000, v239
	v_lshlrev_b32_e32 v240, 4, v240
	v_add_u32_e32 v240, 0x12400, v240
	ds_write_b128 v240, v[236:239]
	s_waitcnt lgkmcnt(0)
	s_barrier
	s_cbranch_scc0 .LBB0_591
	v_lshlrev_b32_e32 v146, 2, v81
	s_movk_i32 s4, 0x100
	v_lshlrev_b32_e64 v174, v146, s4
	s_movk_i32 s4, 0x200
	v_lshlrev_b32_e64 v175, v146, s4
	s_movk_i32 s4, 0x400
	v_lshlrev_b32_e64 v176, v146, s4
	s_movk_i32 s4, 0x800
	v_lshlrev_b32_e64 v177, v146, s4
	s_mov_b32 s4, 0x10000
	v_lshlrev_b32_e64 v178, v146, s4
	s_mov_b32 s4, 0x20000
	v_lshlrev_b32_e64 v179, v146, s4
	s_mov_b32 s4, 0x40000
	v_lshlrev_b32_e64 v180, v146, s4
	s_mov_b32 s4, 0x80000
	v_lshrrev_b32_e32 v16, 3, v80
	v_lshlrev_b32_e64 v181, v146, s4
	s_mov_b32 s4, 0x1000000
	v_xor_b32_e32 v16, v81, v16
	v_lshlrev_b32_e64 v192, v146, s4
	s_brev_b32 s4, 64
	v_lshlrev_b32_e32 v17, 2, v16
	v_lshrrev_b32_e32 v168, 4, v80
	v_xor_b32_e32 v168, v81, v168
	v_lshlrev_b32_e32 v168, 4, v168
	v_lshlrev_b32_e64 v193, v146, s4
	s_brev_b32 s4, 32
	v_add_u32_e32 v16, v145, v80
	v_mov_b32_e32 v30, v1
	v_mov_b32_e32 v31, v1
	v_xor_b32_e32 v165, 8, v17
	v_lshlrev_b32_e64 v194, v146, s4
	s_brev_b32 s4, 16
	v_sub_u32_e32 v196, v16, v146
	v_mov_b32_e32 v16, v1
	v_mov_b32_e32 v17, v1
	v_mov_b32_e32 v18, v1
	v_mov_b32_e32 v19, v1
	v_mov_b32_e32 v20, v1
	v_mov_b32_e32 v21, v1
	v_mov_b32_e32 v22, v1
	v_mov_b32_e32 v23, v1
	v_mov_b32_e32 v24, v1
	v_mov_b32_e32 v25, v1
	v_mov_b32_e32 v26, v1
	v_mov_b32_e32 v27, v1
	v_mov_b32_e32 v28, v1
	v_mov_b32_e32 v29, v1
	v_mov_b64_e32 v[46:47], v[30:31]
	v_mov_b64_e32 v[62:63], v[30:31]
	v_mov_b64_e32 v[78:79], v[30:31]
	s_mov_b32 s30, 2
	v_lshl_add_u32 v166, v81, 4, 0
	v_mad_u32_u24 v167, v80, s60, 0
	v_mul_u32_u24_e32 v169, 0x110, v80
	v_lshlrev_b32_e64 v170, v146, 1
	v_lshlrev_b32_e64 v171, v146, 2
	v_lshlrev_b32_e64 v172, v146, 4
	v_lshlrev_b32_e64 v173, v146, 8
	v_lshlrev_b32_e64 v195, v146, s4
	v_mov_b32_e32 v198, 0
	v_mov_b32_e32 v201, 0xff800000
	s_movk_i32 s31, 0xbf
	v_mov_b64_e32 v[44:45], v[28:29]
	v_mov_b64_e32 v[42:43], v[26:27]
	v_mov_b64_e32 v[40:41], v[24:25]
	v_mov_b64_e32 v[38:39], v[22:23]
	v_mov_b64_e32 v[36:37], v[20:21]
	v_mov_b64_e32 v[34:35], v[18:19]
	v_mov_b64_e32 v[32:33], v[16:17]
	v_mov_b64_e32 v[60:61], v[28:29]
	v_mov_b64_e32 v[58:59], v[26:27]
	v_mov_b64_e32 v[56:57], v[24:25]
	v_mov_b64_e32 v[54:55], v[22:23]
	v_mov_b64_e32 v[52:53], v[20:21]
	v_mov_b64_e32 v[50:51], v[18:19]
	v_mov_b64_e32 v[48:49], v[16:17]
	v_mov_b64_e32 v[76:77], v[28:29]
	v_mov_b64_e32 v[74:75], v[26:27]
	v_mov_b64_e32 v[72:73], v[24:25]
	v_mov_b64_e32 v[70:71], v[22:23]
	v_mov_b64_e32 v[68:69], v[20:21]
	v_mov_b64_e32 v[66:67], v[18:19]
	v_mov_b64_e32 v[64:65], v[16:17]

; #define LAS __attribute__((address_space(3)))
; __device__ __forceinline__ f32x16 mma32(const h16x8 a, const h16x8 b, const f32x16 c) { return __builtin_amdgcn_mfma_f32_32x32x16_f16(a, b, c, 0, 0, 0); }
; __device__ __forceinline__ void dsa_attn_item(CParams& p, LAS unsigned char* lds, int b, int qb, int tid_in, int wave) {
;     ...
;     for (int kt = 0; kt < nkt; ++kt) {
;         const int k0 = kt * 64; const int cur = kt & 1;
;         const LAS h16* Ks = Ks0 + cur * 8704; const LAS h16* Vt = Vt0 + cur * 9216;
;         const unsigned long long mk = mkn; mkn = bmq[kt + 1 < nkt ? kt + 1 : kt];
;         if (kt + 1 < nkt) ATT_STAGE(cur ^ 1, 2048, 2176, kt + 2);
;         if (__ballot(mk != 0ull) != 0ull) {
;             const bool far = (k0 + 63 + 128 <= q0);
;             const float bfar = bdh[128];
; #pragma unroll
;             for (int sub = 0; sub < 2; ++sub) {
;                 const unsigned mw = (unsigned)(mk >> (32 * sub));
;                 if (__ballot(mw != 0u) == 0ull) continue;
;                 f32x16 sc;
; #pragma unroll
;                 for (int i = 0; i < 16; ++i) sc[i] = 0.f;
; #pragma unroll
;                 for (int s = 0; s < 8; ++s) sc = mma32(*(const LAS h16x8*)(Ks + (32 * sub + r) * 136 + 16 * s + 8 * hh), qf[s], sc);
;                 float mx = -INFINITY;
; #pragma unroll
;                 for (int i = 0; i < 16; ++i) { const int ko = (i & 3) + 8 * (i >> 2) + 4 * hh; const int dist = qp - (k0 + 32 * sub + ko);
;                     float bias = bfar; if (!far) bias = bdh[dist < 0 ? 0 : (dist < 128 ? dist : 128)];
;                     const float v = ((mw >> ko) & 1u) ? sc[i] + bias : -INFINITY; sc[i] = v; mx = fmaxf(mx, v); }
.LBB0_514:
	s_waitcnt vmcnt(2)
	v_cmp_ne_u64_e32 vcc, 0, v[150:151]
	s_cbranch_vccz .LBB0_588
	s_and_b32 s4, s34, 1
	s_mul_i32 s5, s4, 0x4400
	s_mulk_i32 s4, 0x4800
	v_add3_u32 v197, v166, v169, s5
	v_add3_u32 v199, v167, v168, s4
	v_readfirstlane_b32 s6, v145
	s_mov_b32 s7, 0x12400
	v_cmp_ne_u32_e32 vcc, 0, v150
	s_cbranch_vccz .LdsaA_s0_skip
	s_mov_b32 s101, 0
.LdsaA_s0_top:
	v_lshrrev_b32_e32 v214, v146, v150
	v_bfe_u32 v227, v214, 0, 4
	v_lshl_add_u32 v227, v227, 4, s7
	ds_read_b128 v[236:239], v227
	v_bfe_u32 v227, v214, 8, 4
	v_lshl_add_u32 v227, v227, 4, s7
	ds_read_b128 v[240:243], v227
	v_bfe_u32 v227, v214, 16, 4
	v_lshl_add_u32 v227, v227, 4, s7
	ds_read_b128 v[244:247], v227
	v_bfe_u32 v227, v214, 24, 4
	v_lshl_add_u32 v227, v227, 4, s7
	ds_read_b128 v[248:251], v227
	ds_read_b128 v[80:83], v197 offset:0
	ds_read_b128 v[84:87], v197 offset:32
	ds_read_b128 v[88:91], v197 offset:64
	ds_read_b128 v[92:95], v197 offset:96
	ds_read_b128 v[202:205], v197 offset:128
	ds_read_b128 v[206:209], v197 offset:160
	ds_read_b128 v[210:213], v197 offset:192
	ds_read_b128 v[228:231], v197 offset:224
	ds_read_b32 v200, v184 offset:512
	s_waitcnt lgkmcnt(5)
	v_mfma_f32_32x32x16_f16 v[236:251], v[80:83], v[112:115], v[236:251]
	v_mfma_f32_32x32x16_f16 v[236:251], v[84:87], v[2:5], v[236:251]
	v_mfma_f32_32x32x16_f16 v[236:251], v[88:91], v[6:9], v[236:251]
	v_mfma_f32_32x32x16_f16 v[236:251], v[92:95], v[10:13], v[236:251]
	s_waitcnt lgkmcnt(1)
	v_mfma_f32_32x32x16_f16 v[236:251], v[202:205], v[96:99], v[236:251]
	v_mfma_f32_32x32x16_f16 v[236:251], v[206:209], v[100:103], v[236:251]
	v_mfma_f32_32x32x16_f16 v[236:251], v[210:213], v[104:107], v[236:251]
	v_mfma_f32_32x32x16_f16 v[236:251], v[228:231], v[108:111], v[236:251]
	s_cmp_le_i32 s31, s6
	s_cbranch_scc1 .LdsaA_s0_far
	v_subrev_u32_e32 v202, 0, v196
	v_med3_i32 v202, v202, 0, v226
	v_lshl_add_u32 v202, v202, 2, v184
	ds_read_b32 v202, v202
	v_subrev_u32_e32 v203, 1, v196
	v_med3_i32 v203, v203, 0, v226
	v_lshl_add_u32 v203, v203, 2, v184
	ds_read_b32 v203, v203
	v_subrev_u32_e32 v204, 2, v196
	v_med3_i32 v204, v204, 0, v226
	v_lshl_add_u32 v204, v204, 2, v184
	ds_read_b32 v204, v204
	v_subrev_u32_e32 v205, 3, v196
	v_med3_i32 v205, v205, 0, v226
	v_lshl_add_u32 v205, v205, 2, v184
	ds_read_b32 v205, v205
	v_subrev_u32_e32 v206, 8, v196
	v_med3_i32 v206, v206, 0, v226
	v_lshl_add_u32 v206, v206, 2, v184
	ds_read_b32 v206, v206
	v_subrev_u32_e32 v207, 9, v196
	v_med3_i32 v207, v207, 0, v226
	v_lshl_add_u32 v207, v207, 2, v184
	ds_read_b32 v207, v207
	v_subrev_u32_e32 v208, 10, v196
	v_med3_i32 v208, v208, 0, v226
	v_lshl_add_u32 v208, v208, 2, v184
	ds_read_b32 v208, v208
	v_subrev_u32_e32 v209, 11, v196
	v_med3_i32 v209, v209, 0, v226
	v_lshl_add_u32 v209, v209, 2, v184
	ds_read_b32 v209, v209
	v_subrev_u32_e32 v210, 16, v196
	v_med3_i32 v210, v210, 0, v226
	v_lshl_add_u32 v210, v210, 2, v184
	ds_read_b32 v210, v210
	v_subrev_u32_e32 v211, 17, v196
	v_med3_i32 v211, v211, 0, v226
	v_lshl_add_u32 v211, v211, 2, v184
	ds_read_b32 v211, v211
	v_subrev_u32_e32 v212, 18, v196
	v_med3_i32 v212, v212, 0, v226
	v_lshl_add_u32 v212, v212, 2, v184
	ds_read_b32 v212, v212
	v_subrev_u32_e32 v213, 19, v196
	v_med3_i32 v213, v213, 0, v226
	v_lshl_add_u32 v213, v213, 2, v184
	ds_read_b32 v213, v213
	v_subrev_u32_e32 v80, 24, v196
	v_med3_i32 v80, v80, 0, v226
	v_lshl_add_u32 v80, v80, 2, v184
	ds_read_b32 v80, v80
	v_subrev_u32_e32 v81, 25, v196
	v_med3_i32 v81, v81, 0, v226
	v_lshl_add_u32 v81, v81, 2, v184
	ds_read_b32 v81, v81
	v_subrev_u32_e32 v82, 26, v196
	v_med3_i32 v82, v82, 0, v226
	v_lshl_add_u32 v82, v82, 2, v184
	ds_read_b32 v82, v82
	v_subrev_u32_e32 v83, 27, v196
	v_med3_i32 v83, v83, 0, v226
	v_lshl_add_u32 v83, v83, 2, v184
	ds_read_b32 v83, v83
	s_waitcnt lgkmcnt(0)
	s_nop 2
	v_add_f32_e32 v236, v236, v202
	v_add_f32_e32 v237, v237, v203
	v_add_f32_e32 v238, v238, v204
	v_add_f32_e32 v239, v239, v205
	v_add_f32_e32 v240, v240, v206
	v_add_f32_e32 v241, v241, v207
	v_add_f32_e32 v242, v242, v208
	v_add_f32_e32 v243, v243, v209
	v_add_f32_e32 v244, v244, v210
	v_add_f32_e32 v245, v245, v211
	v_add_f32_e32 v246, v246, v212
	v_add_f32_e32 v247, v247, v213
	v_add_f32_e32 v248, v248, v80
	v_add_f32_e32 v249, v249, v81
	v_add_f32_e32 v250, v250, v82
	v_add_f32_e32 v251, v251, v83
	v_mov_b32_e32 v200, 0
	s_branch .LdsaA_s0_msk

; __device__ __forceinline__ void dsa_attn_item(CParams& p, LAS unsigned char* lds, int b, int qb, int tid_in, int wave) {
;     ...
; #pragma unroll
;                 for (int i = 0; i < 16; ++i) { const int ko = (i & 3) + 8 * (i >> 2) + 4 * hh; const int dist = qp - (k0 + 32 * sub + ko);
;                     float bias = bfar; if (!far) bias = bdh[dist < 0 ? 0 : (dist < 128 ? dist : 128)];
;                     const float v = ((mw >> ko) & 1u) ? sc[i] + bias : -INFINITY; sc[i] = v; mx = fmaxf(mx, v); }
;                 mx = fmaxf(mx, __shfl_xor(mx, 32));
.LdsaA_s0_msk:
	s_cmp_eq_u32 s100, 0
	s_cbranch_scc1 .LdsaA_s0_slow
	s_waitcnt lgkmcnt(0)
	v_sub_f32_e32 v90, v201, v200

; #define LAS __attribute__((address_space(3)))
; __device__ __forceinline__ f32x16 mma32(const h16x8 a, const h16x8 b, const f32x16 c) { return __builtin_amdgcn_mfma_f32_32x32x16_f16(a, b, c, 0, 0, 0); }
; __device__ __forceinline__ void dsa_attn_item(CParams& p, LAS unsigned char* lds, int b, int qb, int tid_in, int wave) {
;     ...
; #pragma unroll
;             for (int sub = 0; sub < 2; ++sub) {
;                 const unsigned mw = (unsigned)(mk >> (32 * sub));
;                 if (__ballot(mw != 0u) == 0ull) continue;
;                 f32x16 sc;
; #pragma unroll
;                 for (int i = 0; i < 16; ++i) sc[i] = 0.f;
; #pragma unroll
;                 for (int s = 0; s < 8; ++s) sc = mma32(*(const LAS h16x8*)(Ks + (32 * sub + r) * 136 + 16 * s + 8 * hh), qf[s], sc);
;                 float mx = -INFINITY;
; #pragma unroll
;                 for (int i = 0; i < 16; ++i) { const int ko = (i & 3) + 8 * (i >> 2) + 4 * hh; const int dist = qp - (k0 + 32 * sub + ko);
;                     float bias = bfar; if (!far) bias = bdh[dist < 0 ? 0 : (dist < 128 ? dist : 128)];
;                     const float v = ((mw >> ko) & 1u) ? sc[i] + bias : -INFINITY; sc[i] = v; mx = fmaxf(mx, v); }
.LdsaA_s1_top:
	v_lshrrev_b32_e32 v214, v146, v151
	v_bfe_u32 v227, v214, 0, 4
	v_lshl_add_u32 v227, v227, 4, s7
	ds_read_b128 v[236:239], v227
	v_bfe_u32 v227, v214, 8, 4
	v_lshl_add_u32 v227, v227, 4, s7
	ds_read_b128 v[240:243], v227
	v_bfe_u32 v227, v214, 16, 4
	v_lshl_add_u32 v227, v227, 4, s7
	ds_read_b128 v[244:247], v227
	v_bfe_u32 v227, v214, 24, 4
	v_lshl_add_u32 v227, v227, 4, s7
	ds_read_b128 v[248:251], v227
	ds_read_b128 v[80:83], v197 offset:8704
	ds_read_b128 v[84:87], v197 offset:8736
	ds_read_b128 v[88:91], v197 offset:8768
	ds_read_b128 v[92:95], v197 offset:8800
	ds_read_b128 v[202:205], v197 offset:8832
	ds_read_b128 v[206:209], v197 offset:8864
	ds_read_b128 v[210:213], v197 offset:8896
	ds_read_b128 v[228:231], v197 offset:8928
	ds_read_b32 v200, v184 offset:512
	s_waitcnt lgkmcnt(5)
	v_mfma_f32_32x32x16_f16 v[236:251], v[80:83], v[112:115], v[236:251]
	v_mfma_f32_32x32x16_f16 v[236:251], v[84:87], v[2:5], v[236:251]
	v_mfma_f32_32x32x16_f16 v[236:251], v[88:91], v[6:9], v[236:251]
	v_mfma_f32_32x32x16_f16 v[236:251], v[92:95], v[10:13], v[236:251]
	s_waitcnt lgkmcnt(1)
	v_mfma_f32_32x32x16_f16 v[236:251], v[202:205], v[96:99], v[236:251]
	v_mfma_f32_32x32x16_f16 v[236:251], v[206:209], v[100:103], v[236:251]
	v_mfma_f32_32x32x16_f16 v[236:251], v[210:213], v[104:107], v[236:251]
	v_mfma_f32_32x32x16_f16 v[236:251], v[228:231], v[108:111], v[236:251]
	s_cmp_le_i32 s31, s6
	s_cbranch_scc1 .LdsaA_s1_far
	v_subrev_u32_e32 v202, 32, v196
	v_med3_i32 v202, v202, 0, v226
	v_lshl_add_u32 v202, v202, 2, v184
	ds_read_b32 v202, v202
	v_subrev_u32_e32 v203, 33, v196
	v_med3_i32 v203, v203, 0, v226
	v_lshl_add_u32 v203, v203, 2, v184
	ds_read_b32 v203, v203
	v_subrev_u32_e32 v204, 34, v196
	v_med3_i32 v204, v204, 0, v226
	v_lshl_add_u32 v204, v204, 2, v184
	ds_read_b32 v204, v204
	v_subrev_u32_e32 v205, 35, v196
	v_med3_i32 v205, v205, 0, v226
	v_lshl_add_u32 v205, v205, 2, v184
	ds_read_b32 v205, v205
	v_subrev_u32_e32 v206, 40, v196
	v_med3_i32 v206, v206, 0, v226
	v_lshl_add_u32 v206, v206, 2, v184
	ds_read_b32 v206, v206
	v_subrev_u32_e32 v207, 41, v196
	v_med3_i32 v207, v207, 0, v226
	v_lshl_add_u32 v207, v207, 2, v184
	ds_read_b32 v207, v207
	v_subrev_u32_e32 v208, 42, v196
	v_med3_i32 v208, v208, 0, v226
	v_lshl_add_u32 v208, v208, 2, v184
	ds_read_b32 v208, v208
	v_subrev_u32_e32 v209, 43, v196
	v_med3_i32 v209, v209, 0, v226
	v_lshl_add_u32 v209, v209, 2, v184
	ds_read_b32 v209, v209
	v_subrev_u32_e32 v210, 48, v196
	v_med3_i32 v210, v210, 0, v226
	v_lshl_add_u32 v210, v210, 2, v184
	ds_read_b32 v210, v210
	v_subrev_u32_e32 v211, 49, v196
	v_med3_i32 v211, v211, 0, v226
	v_lshl_add_u32 v211, v211, 2, v184
	ds_read_b32 v211, v211
	v_subrev_u32_e32 v212, 50, v196
	v_med3_i32 v212, v212, 0, v226
	v_lshl_add_u32 v212, v212, 2, v184
	ds_read_b32 v212, v212
	v_subrev_u32_e32 v213, 51, v196
	v_med3_i32 v213, v213, 0, v226
	v_lshl_add_u32 v213, v213, 2, v184
	ds_read_b32 v213, v213
	v_subrev_u32_e32 v80, 56, v196
	v_med3_i32 v80, v80, 0, v226
	v_lshl_add_u32 v80, v80, 2, v184
	ds_read_b32 v80, v80
	v_subrev_u32_e32 v81, 57, v196
	v_med3_i32 v81, v81, 0, v226
	v_lshl_add_u32 v81, v81, 2, v184
	ds_read_b32 v81, v81
	v_subrev_u32_e32 v82, 58, v196
	v_med3_i32 v82, v82, 0, v226
	v_lshl_add_u32 v82, v82, 2, v184
	ds_read_b32 v82, v82
	v_subrev_u32_e32 v83, 59, v196
	v_med3_i32 v83, v83, 0, v226
	v_lshl_add_u32 v83, v83, 2, v184
	ds_read_b32 v83, v83
	s_waitcnt lgkmcnt(0)
	s_nop 2
	v_add_f32_e32 v236, v236, v202
	v_add_f32_e32 v237, v237, v203
	v_add_f32_e32 v238, v238, v204
	v_add_f32_e32 v239, v239, v205
	v_add_f32_e32 v240, v240, v206
	v_add_f32_e32 v241, v241, v207
	v_add_f32_e32 v242, v242, v208
	v_add_f32_e32 v243, v243, v209
	v_add_f32_e32 v244, v244, v210
	v_add_f32_e32 v245, v245, v211
	v_add_f32_e32 v246, v246, v212
	v_add_f32_e32 v247, v247, v213
	v_add_f32_e32 v248, v248, v80
	v_add_f32_e32 v249, v249, v81
	v_add_f32_e32 v250, v250, v82
	v_add_f32_e32 v251, v251, v83
	v_mov_b32_e32 v200, 0
	s_branch .LdsaA_s1_msk
